# GEMM4 epilogue: one cache-touch load per thread for the 32 KB output half-tile before the serialized read-modify-write ladder
# speedup vs baseline: 1.0021x; 1.0021x over previous
.LBB0_616:
.Lg4a_epi:
	v_mov_b32_e32 v0, 0
	s_lshl_b32 s22, s14, 18
	s_lshl_b32 s23, s15, 15
	s_add_u32 s22, s22, s23
	s_add_u32 s24, s44, s22
	s_addc_u32 s25, s45, 0
	v_lshlrev_b32_e32 v160, 7, v144
	global_load_dword v161, v160, s[24:25]
	s_waitcnt vmcnt(3)
	v_mov_b32_e32 v80, v144
	s_lshl_b32 s0, s14, 7
	v_lshlrev_b32_e32 v1, 3, v80
	v_lshrrev_b32_e32 v5, 2, v80
	s_waitcnt vmcnt(2)
	v_and_b32_e32 v8, 0x78, v1
	v_lshrrev_b32_e32 v4, 3, v80
	v_and_b32_e32 v5, 0xfffffe0, v5
	v_lshl_or_b32 v1, s15, 7, v8
	v_and_or_b32 v4, v4, 4, v5
	v_ashrrev_i32_e32 v2, 5, v1
	v_and_b32_e32 v1, 0x5f, v80
	v_mul_lo_u32 v4, v4, s13
	v_lshl_add_u32 v1, v1, 2, v4
	v_ashrrev_i32_e32 v4, 3, v80
	v_and_b32_e32 v5, 64, v4
	v_add_u32_e32 v4, s0, v4
	v_ashrrev_i32_e32 v3, 31, v2
	v_ashrrev_i32_e32 v9, 4, v80
	v_ashrrev_i32_e32 v4, 7, v4
	v_lshlrev_b64 v[2:3], 13, v[2:3]
	v_and_or_b32 v6, v9, 31, v5
	v_ashrrev_i32_e32 v5, 31, v4
	s_waitcnt vmcnt(1)
	v_lshl_add_u64 v[10:11], s[44:45], 0, v[2:3]
	v_lshlrev_b64 v[2:3], 18, v[4:5]
	ds_write2_b32 v1, v64, v48 offset1:32
	ds_write2_b32 v1, v65, v49 offset0:132 offset1:164
	v_add_u32_e32 v49, 0x400, v1
	v_add_u32_e32 v64, 0x1000, v1
	v_lshl_add_u64 v[2:3], v[10:11], 0, v[2:3]
	v_lshlrev_b32_e32 v4, 6, v6
	v_mov_b32_e32 v5, v0
	ds_write2_b32 v49, v66, v50 offset0:8 offset1:40
	ds_write2_b32 v49, v67, v51 offset0:140 offset1:172
	ds_write2_b32 v64, v68, v52 offset0:32 offset1:64
	ds_write2_b32 v64, v69, v53 offset0:164 offset1:196
	v_add_u32_e32 v52, 0x1400, v1
	v_lshl_add_u64 v[2:3], v[2:3], 0, v[4:5]
	v_lshlrev_b32_e32 v4, 4, v80
	ds_write2_b32 v52, v70, v54 offset0:40 offset1:72
	ds_write2_b32 v52, v71, v55 offset0:172 offset1:204
	v_add_u32_e32 v53, 0x2000, v1
	v_add_u32_e32 v54, 0x2400, v1
	v_and_b32_e32 v12, 48, v4
	v_mov_b32_e32 v13, v0
	ds_write2_b32 v53, v72, v56 offset0:64 offset1:96
	ds_write2_b32 v53, v73, v57 offset0:196 offset1:228
	ds_write2_b32 v54, v74, v58 offset0:72 offset1:104
	ds_write2_b32 v54, v75, v59 offset0:204 offset1:236
	v_add_u32_e32 v55, 0x3000, v1
	v_add_u32_e32 v56, 0x3200, v1
	v_add_u32_e32 v57, 0x3400, v1
	v_add_u32_e32 v58, 0x3600, v1
	v_lshl_add_u64 v[2:3], v[2:3], 0, v[12:13]
	ds_write2_b32 v55, v76, v60 offset0:96 offset1:128
	ds_write2_b32 v56, v77, v61 offset0:100 offset1:132
	ds_write2_b32 v57, v78, v62 offset0:104 offset1:136
	ds_write2_b32 v58, v79, v63 offset0:108 offset1:140
	s_waitcnt lgkmcnt(0)
	s_barrier
	global_load_dwordx4 v[4:7], v[2:3], off
	v_lshlrev_b32_e32 v48, 2, v8
	v_mad_u64_u32 v[8:9], s[2:3], v9, s13, v[48:49]
	v_add_u32_e32 v14, 0x100, v80
	ds_read_b128 v[60:63], v8
	ds_read_b128 v[66:69], v8 offset:16
	v_ashrrev_i32_e32 v59, 4, v14
	v_ashrrev_i32_e32 v14, 3, v14
	v_and_b32_e32 v50, 64, v14
	v_add_u32_e32 v14, s0, v14
	v_and_or_b32 v9, v59, 31, v50
	v_ashrrev_i32_e32 v50, 7, v14
	v_ashrrev_i32_e32 v51, 31, v50
	v_lshlrev_b64 v[50:51], 18, v[50:51]
	v_mov_b32_e32 v15, v0
	v_lshlrev_b32_e32 v14, 6, v9
	v_lshl_add_u64 v[50:51], v[10:11], 0, v[50:51]
	s_waitcnt vmcnt(0)
	v_lshlrev_b32_e32 v70, 16, v4
	v_and_b32_e32 v71, 0xffff0000, v4
	v_lshlrev_b32_e32 v4, 16, v5
	v_and_b32_e32 v5, 0xffff0000, v5
	v_lshlrev_b32_e32 v72, 16, v6
	v_and_b32_e32 v73, 0xffff0000, v6
	v_lshlrev_b32_e32 v6, 16, v7
	v_and_b32_e32 v7, 0xffff0000, v7
	s_waitcnt lgkmcnt(1)
	v_pk_add_f32 v[60:61], v[60:61], v[70:71]
	v_pk_add_f32 v[62:63], v[62:63], v[4:5]
	s_waitcnt lgkmcnt(0)
	v_pk_add_f32 v[66:67], v[66:67], v[72:73]
	v_pk_add_f32 v[68:69], v[68:69], v[6:7]
	v_cvt_pk_bf16_f32 v4, v60, v61
	v_cvt_pk_bf16_f32 v5, v62, v63
	v_cvt_pk_bf16_f32 v6, v66, v67
	v_cvt_pk_bf16_f32 v7, v68, v69
	global_store_dwordx4 v[2:3], v[4:7], off
	s_nop 1
	v_lshl_add_u64 v[4:5], v[50:51], 0, v[14:15]
	v_lshl_add_u64 v[4:5], v[4:5], 0, v[12:13]
	global_load_dwordx4 v[60:63], v[4:5], off
	v_add_u32_e32 v6, 0x200, v80
	v_ashrrev_i32_e32 v9, 4, v6
	v_ashrrev_i32_e32 v6, 3, v6
	v_and_b32_e32 v50, 64, v6
	v_add_u32_e32 v6, s0, v6
	v_mad_u64_u32 v[14:15], s[2:3], v59, s13, v[48:49]
	v_and_or_b32 v15, v9, 31, v50
	v_ashrrev_i32_e32 v50, 7, v6
	ds_read_b128 v[66:69], v14
	ds_read_b128 v[70:73], v14 offset:16
	v_ashrrev_i32_e32 v51, 31, v50
	v_lshlrev_b64 v[50:51], 18, v[50:51]
	v_mov_b32_e32 v7, v0
	v_lshlrev_b32_e32 v6, 6, v15
	v_lshl_add_u64 v[50:51], v[10:11], 0, v[50:51]
	v_lshl_add_u64 v[6:7], v[50:51], 0, v[6:7]
	v_lshl_add_u64 v[6:7], v[6:7], 0, v[12:13]
	v_add_u32_e32 v15, 0x300, v80
	v_ashrrev_i32_e32 v59, 4, v15
	v_ashrrev_i32_e32 v15, 3, v15
	v_and_b32_e32 v65, 64, v15
	v_add_u32_e32 v15, s0, v15
	s_waitcnt vmcnt(0)
	v_lshlrev_b32_e32 v50, 16, v60
	v_and_b32_e32 v51, 0xffff0000, v60
	v_lshlrev_b32_e32 v60, 16, v61
	v_and_b32_e32 v61, 0xffff0000, v61
	v_lshlrev_b32_e32 v74, 16, v62
	v_and_b32_e32 v75, 0xffff0000, v62
	v_lshlrev_b32_e32 v62, 16, v63
	v_and_b32_e32 v63, 0xffff0000, v63
	s_waitcnt lgkmcnt(1)
	v_pk_add_f32 v[50:51], v[66:67], v[50:51]
	v_pk_add_f32 v[66:67], v[68:69], v[60:61]
	s_waitcnt lgkmcnt(0)
	v_pk_add_f32 v[68:69], v[70:71], v[74:75]
	v_pk_add_f32 v[70:71], v[72:73], v[62:63]
	v_cvt_pk_bf16_f32 v60, v50, v51
	v_cvt_pk_bf16_f32 v61, v66, v67
	v_cvt_pk_bf16_f32 v62, v68, v69
	v_cvt_pk_bf16_f32 v63, v70, v71
	global_store_dwordx4 v[4:5], v[60:63], off
	global_load_dwordx4 v[60:63], v[6:7], off
	v_ashrrev_i32_e32 v66, 7, v15
	v_mad_u64_u32 v[50:51], s[0:1], v9, s13, v[48:49]
	v_ashrrev_i32_e32 v67, 31, v66
	v_lshlrev_b64 v[76:77], 18, v[66:67]
	ds_read_b128 v[66:69], v50
	ds_read_b128 v[70:73], v50 offset:16
	v_and_or_b32 v9, v59, 31, v65
	v_mov_b32_e32 v75, v0
	v_lshlrev_b32_e32 v74, 6, v9
	v_lshl_add_u64 v[10:11], v[10:11], 0, v[76:77]
	v_lshl_add_u64 v[10:11], v[10:11], 0, v[74:75]
	v_lshl_add_u64 v[10:11], v[10:11], 0, v[12:13]
	s_waitcnt vmcnt(0)
	v_lshlrev_b32_e32 v12, 16, v60
	v_and_b32_e32 v13, 0xffff0000, v60
	v_lshlrev_b32_e32 v60, 16, v61
	v_and_b32_e32 v61, 0xffff0000, v61
	v_lshlrev_b32_e32 v74, 16, v62
	v_and_b32_e32 v75, 0xffff0000, v62
	v_lshlrev_b32_e32 v62, 16, v63
	v_and_b32_e32 v63, 0xffff0000, v63
	s_waitcnt lgkmcnt(1)
	v_pk_add_f32 v[12:13], v[66:67], v[12:13]
	v_pk_add_f32 v[66:67], v[68:69], v[60:61]
	s_waitcnt lgkmcnt(0)
	v_pk_add_f32 v[68:69], v[70:71], v[74:75]
	v_pk_add_f32 v[70:71], v[72:73], v[62:63]
	v_cvt_pk_bf16_f32 v60, v12, v13
	v_cvt_pk_bf16_f32 v61, v66, v67
	v_cvt_pk_bf16_f32 v62, v68, v69
	v_cvt_pk_bf16_f32 v63, v70, v71
	global_store_dwordx4 v[6:7], v[60:63], off
	global_load_dwordx4 v[60:63], v[10:11], off
	v_mad_u64_u32 v[12:13], s[0:1], v59, s13, v[48:49]
	ds_read_b128 v[66:69], v12
	ds_read_b128 v[70:73], v12 offset:16
	s_waitcnt vmcnt(0)
	v_lshlrev_b32_e32 v74, 16, v60
	v_and_b32_e32 v75, 0xffff0000, v60
	v_lshlrev_b32_e32 v60, 16, v61
	v_and_b32_e32 v61, 0xffff0000, v61
	v_lshlrev_b32_e32 v76, 16, v62
	v_and_b32_e32 v77, 0xffff0000, v62
	v_lshlrev_b32_e32 v62, 16, v63
	v_and_b32_e32 v63, 0xffff0000, v63
	s_waitcnt lgkmcnt(1)
	v_pk_add_f32 v[66:67], v[66:67], v[74:75]
	v_pk_add_f32 v[68:69], v[68:69], v[60:61]
	s_waitcnt lgkmcnt(0)
	v_pk_add_f32 v[70:71], v[70:71], v[76:77]
	v_pk_add_f32 v[72:73], v[72:73], v[62:63]
	v_cvt_pk_bf16_f32 v60, v66, v67
	v_cvt_pk_bf16_f32 v61, v68, v69
	v_cvt_pk_bf16_f32 v62, v70, v71
	v_cvt_pk_bf16_f32 v63, v72, v73
	global_store_dwordx4 v[10:11], v[60:63], off
	s_barrier
	ds_write2_b32 v1, v32, v16 offset1:32
	ds_write2_b32 v1, v33, v17 offset0:132 offset1:164
	ds_write2_b32 v49, v34, v18 offset0:8 offset1:40
	ds_write2_b32 v49, v35, v19 offset0:140 offset1:172
	ds_write2_b32 v64, v36, v20 offset0:32 offset1:64
	ds_write2_b32 v64, v37, v21 offset0:164 offset1:196
	ds_write2_b32 v52, v38, v22 offset0:40 offset1:72
	ds_write2_b32 v52, v39, v23 offset0:172 offset1:204
	ds_write2_b32 v53, v40, v24 offset0:64 offset1:96
	ds_write2_b32 v53, v41, v25 offset0:196 offset1:228
	ds_write2_b32 v54, v42, v26 offset0:72 offset1:104
	ds_write2_b32 v54, v43, v27 offset0:204 offset1:236
	ds_write2_b32 v55, v44, v28 offset0:96 offset1:128
	ds_write2_b32 v56, v45, v29 offset0:100 offset1:132
	ds_write2_b32 v57, v46, v30 offset0:104 offset1:136
	ds_write2_b32 v58, v47, v31 offset0:108 offset1:140
	s_waitcnt lgkmcnt(0)
	s_barrier
	global_load_dwordx4 v[16:19], v[2:3], off offset:2048
	ds_read_b128 v[20:23], v8
	ds_read_b128 v[24:27], v8 offset:16
	s_waitcnt vmcnt(0)
	v_lshlrev_b32_e32 v8, 16, v16
	v_and_b32_e32 v9, 0xffff0000, v16
	v_lshlrev_b32_e32 v16, 16, v17
	v_and_b32_e32 v17, 0xffff0000, v17
	v_lshlrev_b32_e32 v28, 16, v18
	v_and_b32_e32 v29, 0xffff0000, v18
	v_lshlrev_b32_e32 v18, 16, v19
	v_and_b32_e32 v19, 0xffff0000, v19
	s_waitcnt lgkmcnt(1)
	v_pk_add_f32 v[8:9], v[20:21], v[8:9]
	v_pk_add_f32 v[20:21], v[22:23], v[16:17]
	s_waitcnt lgkmcnt(0)
	v_pk_add_f32 v[22:23], v[24:25], v[28:29]
	v_pk_add_f32 v[24:25], v[26:27], v[18:19]
	v_cvt_pk_bf16_f32 v16, v8, v9
	v_cvt_pk_bf16_f32 v17, v20, v21
	v_cvt_pk_bf16_f32 v18, v22, v23
	v_cvt_pk_bf16_f32 v19, v24, v25
	global_store_dwordx4 v[2:3], v[16:19], off offset:2048
	global_load_dwordx4 v[16:19], v[4:5], off offset:2048
	ds_read_b128 v[20:23], v14
	ds_read_b128 v[24:27], v14 offset:16
	s_waitcnt vmcnt(0)
	v_lshlrev_b32_e32 v2, 16, v16
	v_and_b32_e32 v3, 0xffff0000, v16
	v_lshlrev_b32_e32 v8, 16, v17
	v_and_b32_e32 v9, 0xffff0000, v17
	v_lshlrev_b32_e32 v14, 16, v18
	v_and_b32_e32 v15, 0xffff0000, v18
	v_lshlrev_b32_e32 v16, 16, v19
	v_and_b32_e32 v17, 0xffff0000, v19
	s_waitcnt lgkmcnt(1)
	v_pk_add_f32 v[2:3], v[20:21], v[2:3]
	v_pk_add_f32 v[8:9], v[22:23], v[8:9]
	s_waitcnt lgkmcnt(0)
	v_pk_add_f32 v[18:19], v[24:25], v[14:15]
	v_pk_add_f32 v[20:21], v[26:27], v[16:17]
	v_cvt_pk_bf16_f32 v14, v2, v3
	v_cvt_pk_bf16_f32 v15, v8, v9
	v_cvt_pk_bf16_f32 v16, v18, v19
	v_cvt_pk_bf16_f32 v17, v20, v21
	global_store_dwordx4 v[4:5], v[14:17], off offset:2048
	global_load_dwordx4 v[2:5], v[6:7], off offset:2048
	ds_read_b128 v[14:17], v50
	ds_read_b128 v[18:21], v50 offset:16
	s_waitcnt vmcnt(0)
	v_lshlrev_b32_e32 v8, 16, v2
	v_and_b32_e32 v9, 0xffff0000, v2
	v_lshlrev_b32_e32 v2, 16, v3
	v_and_b32_e32 v3, 0xffff0000, v3
	v_lshlrev_b32_e32 v22, 16, v4
	v_and_b32_e32 v23, 0xffff0000, v4
	v_lshlrev_b32_e32 v4, 16, v5
	v_and_b32_e32 v5, 0xffff0000, v5
	s_waitcnt lgkmcnt(1)
	v_pk_add_f32 v[8:9], v[14:15], v[8:9]
	v_pk_add_f32 v[14:15], v[16:17], v[2:3]
	s_waitcnt lgkmcnt(0)
	v_pk_add_f32 v[16:17], v[18:19], v[22:23]
	v_pk_add_f32 v[18:19], v[20:21], v[4:5]
	v_cvt_pk_bf16_f32 v2, v8, v9
	v_cvt_pk_bf16_f32 v3, v14, v15
	v_cvt_pk_bf16_f32 v4, v16, v17
	v_cvt_pk_bf16_f32 v5, v18, v19
	global_store_dwordx4 v[6:7], v[2:5], off offset:2048
	global_load_dwordx4 v[2:5], v[10:11], off offset:2048
	ds_read_b128 v[6:9], v12
	ds_read_b128 v[12:15], v12 offset:16
	s_waitcnt vmcnt(0)
	v_lshlrev_b32_e32 v16, 16, v2
	v_and_b32_e32 v17, 0xffff0000, v2
	v_lshlrev_b32_e32 v2, 16, v3
	v_and_b32_e32 v3, 0xffff0000, v3
	v_lshlrev_b32_e32 v18, 16, v4
	v_and_b32_e32 v19, 0xffff0000, v4
	v_lshlrev_b32_e32 v4, 16, v5
	v_and_b32_e32 v5, 0xffff0000, v5
	s_waitcnt lgkmcnt(1)
	v_pk_add_f32 v[6:7], v[6:7], v[16:17]
	v_pk_add_f32 v[8:9], v[8:9], v[2:3]
	s_waitcnt lgkmcnt(0)
	v_pk_add_f32 v[12:13], v[12:13], v[18:19]
	v_pk_add_f32 v[14:15], v[14:15], v[4:5]
	v_cvt_pk_bf16_f32 v2, v6, v7
	v_cvt_pk_bf16_f32 v3, v8, v9
	v_cvt_pk_bf16_f32 v4, v12, v13
	v_cvt_pk_bf16_f32 v5, v14, v15
	global_store_dwordx4 v[10:11], v[2:5], off offset:2048

.LBB0_1318:
.Lg4b_epi:
	v_mov_b32_e32 v0, 0
	s_lshl_b32 s22, s16, 18
	s_lshl_b32 s23, s17, 15
	s_add_u32 s22, s22, s23
	s_add_u32 s24, s44, s22
	s_addc_u32 s25, s45, 0
	v_lshlrev_b32_e32 v160, 7, v144
	global_load_dword v161, v160, s[24:25]
	s_waitcnt vmcnt(3)
	v_mov_b32_e32 v80, v144
	s_lshl_b32 s0, s16, 7
	v_lshlrev_b32_e32 v1, 3, v80
	v_lshrrev_b32_e32 v5, 2, v80
	s_waitcnt vmcnt(2)
	v_and_b32_e32 v8, 0x78, v1
	v_lshrrev_b32_e32 v4, 3, v80
	v_and_b32_e32 v5, 0xfffffe0, v5
	v_lshl_or_b32 v1, s17, 7, v8
	v_and_or_b32 v4, v4, 4, v5
	v_ashrrev_i32_e32 v2, 5, v1
	v_and_b32_e32 v1, 0x5f, v80
	v_mul_lo_u32 v4, v4, s15
	v_lshl_add_u32 v1, v1, 2, v4
	v_ashrrev_i32_e32 v4, 3, v80
	v_and_b32_e32 v5, 64, v4
	v_add_u32_e32 v4, s0, v4
	v_ashrrev_i32_e32 v3, 31, v2
	v_ashrrev_i32_e32 v9, 4, v80
	v_ashrrev_i32_e32 v4, 7, v4
	v_lshlrev_b64 v[2:3], 13, v[2:3]
	v_and_or_b32 v6, v9, 31, v5
	v_ashrrev_i32_e32 v5, 31, v4
	s_waitcnt vmcnt(1)
	v_lshl_add_u64 v[10:11], s[44:45], 0, v[2:3]
	v_lshlrev_b64 v[2:3], 18, v[4:5]
	ds_write2_b32 v1, v64, v48 offset1:32
	ds_write2_b32 v1, v65, v49 offset0:132 offset1:164
	v_add_u32_e32 v49, 0x400, v1
	v_add_u32_e32 v64, 0x1000, v1
	v_lshl_add_u64 v[2:3], v[10:11], 0, v[2:3]
	v_lshlrev_b32_e32 v4, 6, v6
	v_mov_b32_e32 v5, v0
	ds_write2_b32 v49, v66, v50 offset0:8 offset1:40
	ds_write2_b32 v49, v67, v51 offset0:140 offset1:172
	ds_write2_b32 v64, v68, v52 offset0:32 offset1:64
	ds_write2_b32 v64, v69, v53 offset0:164 offset1:196
	v_add_u32_e32 v52, 0x1400, v1
	v_lshl_add_u64 v[2:3], v[2:3], 0, v[4:5]
	v_lshlrev_b32_e32 v4, 4, v80
	ds_write2_b32 v52, v70, v54 offset0:40 offset1:72
	ds_write2_b32 v52, v71, v55 offset0:172 offset1:204
	v_add_u32_e32 v53, 0x2000, v1
	v_add_u32_e32 v54, 0x2400, v1
	v_and_b32_e32 v12, 48, v4
	v_mov_b32_e32 v13, v0
	ds_write2_b32 v53, v72, v56 offset0:64 offset1:96
	ds_write2_b32 v53, v73, v57 offset0:196 offset1:228
	ds_write2_b32 v54, v74, v58 offset0:72 offset1:104
	ds_write2_b32 v54, v75, v59 offset0:204 offset1:236
	v_add_u32_e32 v55, 0x3000, v1
	v_add_u32_e32 v56, 0x3200, v1
	v_add_u32_e32 v57, 0x3400, v1
	v_add_u32_e32 v58, 0x3600, v1
	v_lshl_add_u64 v[2:3], v[2:3], 0, v[12:13]
	ds_write2_b32 v55, v76, v60 offset0:96 offset1:128
	ds_write2_b32 v56, v77, v61 offset0:100 offset1:132
	ds_write2_b32 v57, v78, v62 offset0:104 offset1:136
	ds_write2_b32 v58, v79, v63 offset0:108 offset1:140
	s_waitcnt lgkmcnt(0)
	s_barrier
	global_load_dwordx4 v[4:7], v[2:3], off
	v_lshlrev_b32_e32 v48, 2, v8
	v_mad_u64_u32 v[8:9], s[2:3], v9, s15, v[48:49]
	v_add_u32_e32 v14, 0x100, v80
	ds_read_b128 v[60:63], v8
	ds_read_b128 v[66:69], v8 offset:16
	v_ashrrev_i32_e32 v59, 4, v14
	v_ashrrev_i32_e32 v14, 3, v14
	v_and_b32_e32 v50, 64, v14
	v_add_u32_e32 v14, s0, v14
	v_and_or_b32 v9, v59, 31, v50
	v_ashrrev_i32_e32 v50, 7, v14
	v_ashrrev_i32_e32 v51, 31, v50
	v_lshlrev_b64 v[50:51], 18, v[50:51]
	v_mov_b32_e32 v15, v0
	v_lshlrev_b32_e32 v14, 6, v9
	v_lshl_add_u64 v[50:51], v[10:11], 0, v[50:51]
	s_waitcnt vmcnt(0)
	v_lshlrev_b32_e32 v70, 16, v4
	v_and_b32_e32 v71, 0xffff0000, v4
	v_lshlrev_b32_e32 v4, 16, v5
	v_and_b32_e32 v5, 0xffff0000, v5
	v_lshlrev_b32_e32 v72, 16, v6
	v_and_b32_e32 v73, 0xffff0000, v6
	v_lshlrev_b32_e32 v6, 16, v7
	v_and_b32_e32 v7, 0xffff0000, v7
	s_waitcnt lgkmcnt(1)
	v_pk_add_f32 v[60:61], v[60:61], v[70:71]
	v_pk_add_f32 v[62:63], v[62:63], v[4:5]
	s_waitcnt lgkmcnt(0)
	v_pk_add_f32 v[66:67], v[66:67], v[72:73]
	v_pk_add_f32 v[68:69], v[68:69], v[6:7]
	v_cvt_pk_bf16_f32 v4, v60, v61
	v_cvt_pk_bf16_f32 v5, v62, v63
	v_cvt_pk_bf16_f32 v6, v66, v67
	v_cvt_pk_bf16_f32 v7, v68, v69
	global_store_dwordx4 v[2:3], v[4:7], off
	s_nop 1
	v_lshl_add_u64 v[4:5], v[50:51], 0, v[14:15]
	v_lshl_add_u64 v[4:5], v[4:5], 0, v[12:13]
	global_load_dwordx4 v[60:63], v[4:5], off
	v_add_u32_e32 v6, 0x200, v80
	v_ashrrev_i32_e32 v9, 4, v6
	v_ashrrev_i32_e32 v6, 3, v6
	v_and_b32_e32 v50, 64, v6
	v_add_u32_e32 v6, s0, v6
	v_mad_u64_u32 v[14:15], s[2:3], v59, s15, v[48:49]
	v_and_or_b32 v15, v9, 31, v50
	v_ashrrev_i32_e32 v50, 7, v6
	ds_read_b128 v[66:69], v14
	ds_read_b128 v[70:73], v14 offset:16
	v_ashrrev_i32_e32 v51, 31, v50
	v_lshlrev_b64 v[50:51], 18, v[50:51]
	v_mov_b32_e32 v7, v0
	v_lshlrev_b32_e32 v6, 6, v15
	v_lshl_add_u64 v[50:51], v[10:11], 0, v[50:51]
	v_lshl_add_u64 v[6:7], v[50:51], 0, v[6:7]
	v_lshl_add_u64 v[6:7], v[6:7], 0, v[12:13]
	v_add_u32_e32 v15, 0x300, v80
	v_ashrrev_i32_e32 v59, 4, v15
	v_ashrrev_i32_e32 v15, 3, v15
	v_and_b32_e32 v65, 64, v15
	v_add_u32_e32 v15, s0, v15
	s_waitcnt vmcnt(0)
	v_lshlrev_b32_e32 v50, 16, v60
	v_and_b32_e32 v51, 0xffff0000, v60
	v_lshlrev_b32_e32 v60, 16, v61
	v_and_b32_e32 v61, 0xffff0000, v61
	v_lshlrev_b32_e32 v74, 16, v62
	v_and_b32_e32 v75, 0xffff0000, v62
	v_lshlrev_b32_e32 v62, 16, v63
	v_and_b32_e32 v63, 0xffff0000, v63
	s_waitcnt lgkmcnt(1)
	v_pk_add_f32 v[50:51], v[66:67], v[50:51]
	v_pk_add_f32 v[66:67], v[68:69], v[60:61]
	s_waitcnt lgkmcnt(0)
	v_pk_add_f32 v[68:69], v[70:71], v[74:75]
	v_pk_add_f32 v[70:71], v[72:73], v[62:63]
	v_cvt_pk_bf16_f32 v60, v50, v51
	v_cvt_pk_bf16_f32 v61, v66, v67
	v_cvt_pk_bf16_f32 v62, v68, v69
	v_cvt_pk_bf16_f32 v63, v70, v71
	global_store_dwordx4 v[4:5], v[60:63], off
	global_load_dwordx4 v[60:63], v[6:7], off
	v_ashrrev_i32_e32 v66, 7, v15
	v_mad_u64_u32 v[50:51], s[0:1], v9, s15, v[48:49]
	v_ashrrev_i32_e32 v67, 31, v66
	v_lshlrev_b64 v[76:77], 18, v[66:67]
	ds_read_b128 v[66:69], v50
	ds_read_b128 v[70:73], v50 offset:16
	v_and_or_b32 v9, v59, 31, v65
	v_mov_b32_e32 v75, v0
	v_lshlrev_b32_e32 v74, 6, v9
	v_lshl_add_u64 v[10:11], v[10:11], 0, v[76:77]
	v_lshl_add_u64 v[10:11], v[10:11], 0, v[74:75]
	v_lshl_add_u64 v[10:11], v[10:11], 0, v[12:13]
	s_waitcnt vmcnt(0)
	v_lshlrev_b32_e32 v12, 16, v60
	v_and_b32_e32 v13, 0xffff0000, v60
	v_lshlrev_b32_e32 v60, 16, v61
	v_and_b32_e32 v61, 0xffff0000, v61
	v_lshlrev_b32_e32 v74, 16, v62
	v_and_b32_e32 v75, 0xffff0000, v62
	v_lshlrev_b32_e32 v62, 16, v63
	v_and_b32_e32 v63, 0xffff0000, v63
	s_waitcnt lgkmcnt(1)
	v_pk_add_f32 v[12:13], v[66:67], v[12:13]
	v_pk_add_f32 v[66:67], v[68:69], v[60:61]
	s_waitcnt lgkmcnt(0)
	v_pk_add_f32 v[68:69], v[70:71], v[74:75]
	v_pk_add_f32 v[70:71], v[72:73], v[62:63]
	v_cvt_pk_bf16_f32 v60, v12, v13
	v_cvt_pk_bf16_f32 v61, v66, v67
	v_cvt_pk_bf16_f32 v62, v68, v69
	v_cvt_pk_bf16_f32 v63, v70, v71
	global_store_dwordx4 v[6:7], v[60:63], off
	global_load_dwordx4 v[60:63], v[10:11], off
	v_mad_u64_u32 v[12:13], s[0:1], v59, s15, v[48:49]
	ds_read_b128 v[66:69], v12
	ds_read_b128 v[70:73], v12 offset:16
	s_waitcnt vmcnt(0)
	v_lshlrev_b32_e32 v74, 16, v60
	v_and_b32_e32 v75, 0xffff0000, v60
	v_lshlrev_b32_e32 v60, 16, v61
	v_and_b32_e32 v61, 0xffff0000, v61
	v_lshlrev_b32_e32 v76, 16, v62
	v_and_b32_e32 v77, 0xffff0000, v62
	v_lshlrev_b32_e32 v62, 16, v63
	v_and_b32_e32 v63, 0xffff0000, v63
	s_waitcnt lgkmcnt(1)
	v_pk_add_f32 v[66:67], v[66:67], v[74:75]
	v_pk_add_f32 v[68:69], v[68:69], v[60:61]
	s_waitcnt lgkmcnt(0)
	v_pk_add_f32 v[70:71], v[70:71], v[76:77]
	v_pk_add_f32 v[72:73], v[72:73], v[62:63]
	v_cvt_pk_bf16_f32 v60, v66, v67
	v_cvt_pk_bf16_f32 v61, v68, v69
	v_cvt_pk_bf16_f32 v62, v70, v71
	v_cvt_pk_bf16_f32 v63, v72, v73
	global_store_dwordx4 v[10:11], v[60:63], off
	s_barrier
	ds_write2_b32 v1, v32, v16 offset1:32
	ds_write2_b32 v1, v33, v17 offset0:132 offset1:164
	ds_write2_b32 v49, v34, v18 offset0:8 offset1:40
	ds_write2_b32 v49, v35, v19 offset0:140 offset1:172
	ds_write2_b32 v64, v36, v20 offset0:32 offset1:64
	ds_write2_b32 v64, v37, v21 offset0:164 offset1:196
	ds_write2_b32 v52, v38, v22 offset0:40 offset1:72
	ds_write2_b32 v52, v39, v23 offset0:172 offset1:204
	ds_write2_b32 v53, v40, v24 offset0:64 offset1:96
	ds_write2_b32 v53, v41, v25 offset0:196 offset1:228
	ds_write2_b32 v54, v42, v26 offset0:72 offset1:104
	ds_write2_b32 v54, v43, v27 offset0:204 offset1:236
	ds_write2_b32 v55, v44, v28 offset0:96 offset1:128
	ds_write2_b32 v56, v45, v29 offset0:100 offset1:132
	ds_write2_b32 v57, v46, v30 offset0:104 offset1:136
	ds_write2_b32 v58, v47, v31 offset0:108 offset1:140
	s_waitcnt lgkmcnt(0)
	s_barrier
	global_load_dwordx4 v[16:19], v[2:3], off offset:2048
	ds_read_b128 v[20:23], v8
	ds_read_b128 v[24:27], v8 offset:16
	s_waitcnt vmcnt(0)
	v_lshlrev_b32_e32 v8, 16, v16
	v_and_b32_e32 v9, 0xffff0000, v16
	v_lshlrev_b32_e32 v16, 16, v17
	v_and_b32_e32 v17, 0xffff0000, v17
	v_lshlrev_b32_e32 v28, 16, v18
	v_and_b32_e32 v29, 0xffff0000, v18
	v_lshlrev_b32_e32 v18, 16, v19
	v_and_b32_e32 v19, 0xffff0000, v19
	s_waitcnt lgkmcnt(1)
	v_pk_add_f32 v[8:9], v[20:21], v[8:9]
	v_pk_add_f32 v[20:21], v[22:23], v[16:17]
	s_waitcnt lgkmcnt(0)
	v_pk_add_f32 v[22:23], v[24:25], v[28:29]
	v_pk_add_f32 v[24:25], v[26:27], v[18:19]
	v_cvt_pk_bf16_f32 v16, v8, v9
	v_cvt_pk_bf16_f32 v17, v20, v21
	v_cvt_pk_bf16_f32 v18, v22, v23
	v_cvt_pk_bf16_f32 v19, v24, v25
	global_store_dwordx4 v[2:3], v[16:19], off offset:2048
	global_load_dwordx4 v[16:19], v[4:5], off offset:2048
	ds_read_b128 v[20:23], v14
	ds_read_b128 v[24:27], v14 offset:16
	s_waitcnt vmcnt(0)
	v_lshlrev_b32_e32 v2, 16, v16
	v_and_b32_e32 v3, 0xffff0000, v16
	v_lshlrev_b32_e32 v8, 16, v17
	v_and_b32_e32 v9, 0xffff0000, v17
	v_lshlrev_b32_e32 v14, 16, v18
	v_and_b32_e32 v15, 0xffff0000, v18
	v_lshlrev_b32_e32 v16, 16, v19
	v_and_b32_e32 v17, 0xffff0000, v19
	s_waitcnt lgkmcnt(1)
	v_pk_add_f32 v[2:3], v[20:21], v[2:3]
	v_pk_add_f32 v[8:9], v[22:23], v[8:9]
	s_waitcnt lgkmcnt(0)
	v_pk_add_f32 v[18:19], v[24:25], v[14:15]
	v_pk_add_f32 v[20:21], v[26:27], v[16:17]
	v_cvt_pk_bf16_f32 v14, v2, v3
	v_cvt_pk_bf16_f32 v15, v8, v9
	v_cvt_pk_bf16_f32 v16, v18, v19
	v_cvt_pk_bf16_f32 v17, v20, v21
	global_store_dwordx4 v[4:5], v[14:17], off offset:2048
	global_load_dwordx4 v[2:5], v[6:7], off offset:2048
	ds_read_b128 v[14:17], v50
	ds_read_b128 v[18:21], v50 offset:16
	s_waitcnt vmcnt(0)
	v_lshlrev_b32_e32 v8, 16, v2
	v_and_b32_e32 v9, 0xffff0000, v2
	v_lshlrev_b32_e32 v2, 16, v3
	v_and_b32_e32 v3, 0xffff0000, v3
	v_lshlrev_b32_e32 v22, 16, v4
	v_and_b32_e32 v23, 0xffff0000, v4
	v_lshlrev_b32_e32 v4, 16, v5
	v_and_b32_e32 v5, 0xffff0000, v5
	s_waitcnt lgkmcnt(1)
	v_pk_add_f32 v[8:9], v[14:15], v[8:9]
	v_pk_add_f32 v[14:15], v[16:17], v[2:3]
	s_waitcnt lgkmcnt(0)
	v_pk_add_f32 v[16:17], v[18:19], v[22:23]
	v_pk_add_f32 v[18:19], v[20:21], v[4:5]
	v_cvt_pk_bf16_f32 v2, v8, v9
	v_cvt_pk_bf16_f32 v3, v14, v15
	v_cvt_pk_bf16_f32 v4, v16, v17
	v_cvt_pk_bf16_f32 v5, v18, v19
	global_store_dwordx4 v[6:7], v[2:5], off offset:2048
	global_load_dwordx4 v[2:5], v[10:11], off offset:2048
	ds_read_b128 v[6:9], v12
	ds_read_b128 v[12:15], v12 offset:16
	s_waitcnt vmcnt(0)
	v_lshlrev_b32_e32 v16, 16, v2
	v_and_b32_e32 v17, 0xffff0000, v2
	v_lshlrev_b32_e32 v2, 16, v3
	v_and_b32_e32 v3, 0xffff0000, v3
	v_lshlrev_b32_e32 v18, 16, v4
	v_and_b32_e32 v19, 0xffff0000, v4
	v_lshlrev_b32_e32 v4, 16, v5
	v_and_b32_e32 v5, 0xffff0000, v5
	s_waitcnt lgkmcnt(1)
	v_pk_add_f32 v[6:7], v[6:7], v[16:17]
	v_pk_add_f32 v[8:9], v[8:9], v[2:3]
	s_waitcnt lgkmcnt(0)
	v_pk_add_f32 v[12:13], v[12:13], v[18:19]
	v_pk_add_f32 v[14:15], v[14:15], v[4:5]
	v_cvt_pk_bf16_f32 v2, v6, v7
	v_cvt_pk_bf16_f32 v3, v8, v9
	v_cvt_pk_bf16_f32 v4, v12, v13
	v_cvt_pk_bf16_f32 v5, v14, v15
	global_store_dwordx4 v[10:11], v[2:5], off offset:2048
